# w_in narrow strip: no LDS K loop, each wave multiplies a quarter of K straight from global into registers, partial sums added through LDS
# speedup vs baseline: 1.0152x; 1.0025x over previous
.Lg2_win_next:
	s_add_i32 s64, s64, 1
	s_cmp_lt_u32 s64, 7
	s_cbranch_scc1 .Lg2_win_tile
	v_lshrrev_b32_e32 v4, 6, v163
	v_and_b32_e32 v5, 63, v163
	v_and_b32_e32 v6, 15, v5
	v_lshrrev_b32_e32 v7, 4, v5
	v_lshlrev_b32_e32 v11, 1, v4
	s_mov_b32 s2, 0x8000
	v_mul_lo_u32 v12, v11, s2
	v_lshl_add_u32 v160, v5, 4, v12
	v_add_u32_e32 v161, 0x8000, v160
	v_lshrrev_b32_e32 v12, 1, v7
	v_lshl_add_u32 v12, v11, 1, v12
	v_and_b32_e32 v13, 1, v7
	v_lshlrev_b32_e32 v13, 3, v13
	v_lshl_add_u32 v14, v6, 8, v13
	v_xor_b32_e32 v15, v12, v6
	v_lshlrev_b32_e32 v15, 4, v15
	v_add_u32_e32 v212, v14, v15
	v_add_u32_e32 v12, 2, v12
	v_xor_b32_e32 v15, v12, v6
	v_lshlrev_b32_e32 v15, 4, v15
	v_add_u32_e32 v213, v14, v15
	v_add_u32_e32 v253, 0x8000, v212
	v_add_u32_e32 v254, 0x8000, v213
	s_mov_b32 s38, 56
	s_lshl_b32 s0, s68, 5
	s_add_i32 s69, s42, s0
	s_cmp_eq_u32 s68, 7
	s_cselect_b32 s0, 1, 0
	s_and_b32 s65, s0, s43
	s_lshl_b32 s0, s38, 7
	s_mul_i32 s2, s69, 0x800
	s_mul_hi_u32 s3, s69, 0x800
	s_add_u32 s56, s26, s2
	s_addc_u32 s57, s27, s3
	s_add_u32 s56, s56, 0x11140000
	s_addc_u32 s57, s57, 0
	s_mul_i32 s2, s0, 0x800
	s_mul_hi_u32 s3, s0, 0x800
	s_add_u32 s58, s26, s2
	s_addc_u32 s59, s27, s3
	s_add_u32 s58, s58, 0xeb20000
	s_addc_u32 s59, s59, 0
	s_mul_i32 s2, s69, 0x3900
	s_mul_hi_u32 s3, s69, 0x3900
	s_lshl_b32 s0, s0, 1
	s_add_u32 s2, s2, s0
	s_addc_u32 s3, s3, 0
	s_add_u32 s60, s26, s2
	s_addc_u32 s61, s27, s3
	s_add_u32 s60, s60, 0x0
	s_addc_u32 s61, s61, 0
	s_mov_b32 s0, 0x800
	v_mul_lo_u32 v8, v6, s0
	v_lshl_add_u32 v8, v7, 4, v8
	v_lshl_add_u32 v8, v4, 9, v8
	v_lshlrev_b32_e32 v9, 4, v5
	v_lshl_add_u32 v9, v4, 13, v9
	v_add_u32_e32 v10, 0x1000, v9
	s_add_u32 s2, s56, 0x8000
	s_addc_u32 s3, s57, 0
	s_add_u32 s4, s2, 0x8000
	s_addc_u32 s5, s3, 0
	s_add_u32 s40, s58, 0x8000
	s_addc_u32 s41, s59, 0
	global_load_dwordx4 v[36:39], v9, s[58:59] offset:0
	global_load_dwordx4 v[40:43], v9, s[40:41] offset:0
	global_load_dwordx4 v[24:27], v8, s[56:57] offset:0
	global_load_dwordx4 v[28:31], v8, s[2:3] offset:0
	global_load_dwordx4 v[32:35], v8, s[4:5] offset:0
	global_load_dwordx4 v[56:59], v9, s[58:59] offset:1024
	global_load_dwordx4 v[60:63], v9, s[40:41] offset:1024
	global_load_dwordx4 v[44:47], v8, s[56:57] offset:64
	global_load_dwordx4 v[48:51], v8, s[2:3] offset:64
	global_load_dwordx4 v[52:55], v8, s[4:5] offset:64
	global_load_dwordx4 v[76:79], v9, s[58:59] offset:2048
	global_load_dwordx4 v[80:83], v9, s[40:41] offset:2048
	global_load_dwordx4 v[64:67], v8, s[56:57] offset:128
	global_load_dwordx4 v[68:71], v8, s[2:3] offset:128
	global_load_dwordx4 v[72:75], v8, s[4:5] offset:128
	global_load_dwordx4 v[96:99], v9, s[58:59] offset:3072
	global_load_dwordx4 v[100:103], v9, s[40:41] offset:3072
	global_load_dwordx4 v[84:87], v8, s[56:57] offset:192
	global_load_dwordx4 v[88:91], v8, s[2:3] offset:192
	global_load_dwordx4 v[92:95], v8, s[4:5] offset:192
	global_load_dwordx4 v[116:119], v10, s[58:59] offset:0
	global_load_dwordx4 v[120:123], v10, s[40:41] offset:0
	global_load_dwordx4 v[104:107], v8, s[56:57] offset:256
	global_load_dwordx4 v[108:111], v8, s[2:3] offset:256
	global_load_dwordx4 v[112:115], v8, s[4:5] offset:256
	global_load_dwordx4 v[164:167], v10, s[58:59] offset:1024
	global_load_dwordx4 v[168:171], v10, s[40:41] offset:1024
	global_load_dwordx4 v[124:127], v8, s[56:57] offset:320
	global_load_dwordx4 v[128:131], v8, s[2:3] offset:320
	global_load_dwordx4 v[132:135], v8, s[4:5] offset:320
	global_load_dwordx4 v[184:187], v10, s[58:59] offset:2048
	global_load_dwordx4 v[188:191], v10, s[40:41] offset:2048
	global_load_dwordx4 v[172:175], v8, s[56:57] offset:384
	global_load_dwordx4 v[176:179], v8, s[2:3] offset:384
	global_load_dwordx4 v[180:183], v8, s[4:5] offset:384
	global_load_dwordx4 v[204:207], v10, s[58:59] offset:3072
	global_load_dwordx4 v[208:211], v10, s[40:41] offset:3072
	global_load_dwordx4 v[192:195], v8, s[56:57] offset:448
	global_load_dwordx4 v[196:199], v8, s[2:3] offset:448
	global_load_dwordx4 v[200:203], v8, s[4:5] offset:448
	v_mov_b32_e32 v0, 0
	v_mov_b32_e32 v1, 0
	v_mov_b32_e32 v2, 0
	v_mov_b32_e32 v3, 0
	v_mov_b32_e32 v4, 0
	v_mov_b32_e32 v5, 0
	v_mov_b32_e32 v6, 0
	v_mov_b32_e32 v7, 0
	v_mov_b32_e32 v8, 0
	v_mov_b32_e32 v9, 0
	v_mov_b32_e32 v10, 0
	v_mov_b32_e32 v11, 0
	v_mov_b32_e32 v12, 0
	v_mov_b32_e32 v13, 0
	v_mov_b32_e32 v14, 0
	v_mov_b32_e32 v15, 0
	v_mov_b32_e32 v16, 0
	v_mov_b32_e32 v17, 0
	v_mov_b32_e32 v18, 0
	v_mov_b32_e32 v19, 0
	v_mov_b32_e32 v20, 0
	v_mov_b32_e32 v21, 0
	v_mov_b32_e32 v22, 0
	v_mov_b32_e32 v23, 0
	s_waitcnt vmcnt(35)
	v_mfma_f32_16x16x32_bf16 v[0:3], v[36:39], v[24:27], v[0:3]
	v_mfma_f32_16x16x32_bf16 v[4:7], v[40:43], v[24:27], v[4:7]
	v_mfma_f32_16x16x32_bf16 v[8:11], v[36:39], v[28:31], v[8:11]
	v_mfma_f32_16x16x32_bf16 v[12:15], v[40:43], v[28:31], v[12:15]
	v_mfma_f32_16x16x32_bf16 v[16:19], v[36:39], v[32:35], v[16:19]
	v_mfma_f32_16x16x32_bf16 v[20:23], v[40:43], v[32:35], v[20:23]
	s_waitcnt vmcnt(30)
	v_mfma_f32_16x16x32_bf16 v[0:3], v[56:59], v[44:47], v[0:3]
	v_mfma_f32_16x16x32_bf16 v[4:7], v[60:63], v[44:47], v[4:7]
	v_mfma_f32_16x16x32_bf16 v[8:11], v[56:59], v[48:51], v[8:11]
	v_mfma_f32_16x16x32_bf16 v[12:15], v[60:63], v[48:51], v[12:15]
	v_mfma_f32_16x16x32_bf16 v[16:19], v[56:59], v[52:55], v[16:19]
	v_mfma_f32_16x16x32_bf16 v[20:23], v[60:63], v[52:55], v[20:23]
	s_waitcnt vmcnt(25)
	v_mfma_f32_16x16x32_bf16 v[0:3], v[76:79], v[64:67], v[0:3]
	v_mfma_f32_16x16x32_bf16 v[4:7], v[80:83], v[64:67], v[4:7]
	v_mfma_f32_16x16x32_bf16 v[8:11], v[76:79], v[68:71], v[8:11]
	v_mfma_f32_16x16x32_bf16 v[12:15], v[80:83], v[68:71], v[12:15]
	v_mfma_f32_16x16x32_bf16 v[16:19], v[76:79], v[72:75], v[16:19]
	v_mfma_f32_16x16x32_bf16 v[20:23], v[80:83], v[72:75], v[20:23]
	s_waitcnt vmcnt(20)
	v_mfma_f32_16x16x32_bf16 v[0:3], v[96:99], v[84:87], v[0:3]
	v_mfma_f32_16x16x32_bf16 v[4:7], v[100:103], v[84:87], v[4:7]
	v_mfma_f32_16x16x32_bf16 v[8:11], v[96:99], v[88:91], v[8:11]
	v_mfma_f32_16x16x32_bf16 v[12:15], v[100:103], v[88:91], v[12:15]
	v_mfma_f32_16x16x32_bf16 v[16:19], v[96:99], v[92:95], v[16:19]
	v_mfma_f32_16x16x32_bf16 v[20:23], v[100:103], v[92:95], v[20:23]
	s_waitcnt vmcnt(15)
	v_mfma_f32_16x16x32_bf16 v[0:3], v[116:119], v[104:107], v[0:3]
	v_mfma_f32_16x16x32_bf16 v[4:7], v[120:123], v[104:107], v[4:7]
	v_mfma_f32_16x16x32_bf16 v[8:11], v[116:119], v[108:111], v[8:11]
	v_mfma_f32_16x16x32_bf16 v[12:15], v[120:123], v[108:111], v[12:15]
	v_mfma_f32_16x16x32_bf16 v[16:19], v[116:119], v[112:115], v[16:19]
	v_mfma_f32_16x16x32_bf16 v[20:23], v[120:123], v[112:115], v[20:23]
	s_waitcnt vmcnt(10)
	v_mfma_f32_16x16x32_bf16 v[0:3], v[164:167], v[124:127], v[0:3]
	v_mfma_f32_16x16x32_bf16 v[4:7], v[168:171], v[124:127], v[4:7]
	v_mfma_f32_16x16x32_bf16 v[8:11], v[164:167], v[128:131], v[8:11]
	v_mfma_f32_16x16x32_bf16 v[12:15], v[168:171], v[128:131], v[12:15]
	v_mfma_f32_16x16x32_bf16 v[16:19], v[164:167], v[132:135], v[16:19]
	v_mfma_f32_16x16x32_bf16 v[20:23], v[168:171], v[132:135], v[20:23]
	s_waitcnt vmcnt(5)
	v_mfma_f32_16x16x32_bf16 v[0:3], v[184:187], v[172:175], v[0:3]
	v_mfma_f32_16x16x32_bf16 v[4:7], v[188:191], v[172:175], v[4:7]
	v_mfma_f32_16x16x32_bf16 v[8:11], v[184:187], v[176:179], v[8:11]
	v_mfma_f32_16x16x32_bf16 v[12:15], v[188:191], v[176:179], v[12:15]
	v_mfma_f32_16x16x32_bf16 v[16:19], v[184:187], v[180:183], v[16:19]
	v_mfma_f32_16x16x32_bf16 v[20:23], v[188:191], v[180:183], v[20:23]
	s_waitcnt vmcnt(0)
	v_mfma_f32_16x16x32_bf16 v[0:3], v[204:207], v[192:195], v[0:3]
	v_mfma_f32_16x16x32_bf16 v[4:7], v[208:211], v[192:195], v[4:7]
	v_mfma_f32_16x16x32_bf16 v[8:11], v[204:207], v[196:199], v[8:11]
	v_mfma_f32_16x16x32_bf16 v[12:15], v[208:211], v[196:199], v[12:15]
	v_mfma_f32_16x16x32_bf16 v[16:19], v[204:207], v[200:203], v[16:19]
	v_mfma_f32_16x16x32_bf16 v[20:23], v[208:211], v[200:203], v[20:23]
	s_nop 7
	s_nop 7
	v_lshlrev_b32_e32 v24, 4, v5
	s_mul_i32 s0, s70, 0x1800
	v_add_u32_e32 v25, s0, v24
	ds_write_b128 v25, v[0:3] offset:0
	ds_write_b128 v25, v[4:7] offset:1024
	ds_write_b128 v25, v[8:11] offset:2048
	ds_write_b128 v25, v[12:15] offset:3072
	ds_write_b128 v25, v[16:19] offset:4096
	ds_write_b128 v25, v[20:23] offset:5120
	s_waitcnt lgkmcnt(0)
	s_barrier
	s_cmp_lg_u32 s70, 0
	s_cbranch_scc1 .Lg2_win_sd_clr
	ds_read_b128 v[28:31], v24 offset:6144
	ds_read_b128 v[32:35], v24 offset:7168
	ds_read_b128 v[36:39], v24 offset:8192
	ds_read_b128 v[40:43], v24 offset:9216
	ds_read_b128 v[44:47], v24 offset:10240
	ds_read_b128 v[48:51], v24 offset:11264
	ds_read_b128 v[52:55], v24 offset:12288
	ds_read_b128 v[56:59], v24 offset:13312
	ds_read_b128 v[60:63], v24 offset:14336
	ds_read_b128 v[64:67], v24 offset:15360
	ds_read_b128 v[68:71], v24 offset:16384
	ds_read_b128 v[72:75], v24 offset:17408
	ds_read_b128 v[76:79], v24 offset:18432
	ds_read_b128 v[80:83], v24 offset:19456
	ds_read_b128 v[84:87], v24 offset:20480
	ds_read_b128 v[88:91], v24 offset:21504
	ds_read_b128 v[92:95], v24 offset:22528
	ds_read_b128 v[96:99], v24 offset:23552
	s_waitcnt lgkmcnt(12)
	v_add_f32_e32 v0, v0, v28
	v_add_f32_e32 v1, v1, v29
	v_add_f32_e32 v2, v2, v30
	v_add_f32_e32 v3, v3, v31
	v_add_f32_e32 v4, v4, v32
	v_add_f32_e32 v5, v5, v33
	v_add_f32_e32 v6, v6, v34
	v_add_f32_e32 v7, v7, v35
	v_add_f32_e32 v8, v8, v36
	v_add_f32_e32 v9, v9, v37
	v_add_f32_e32 v10, v10, v38
	v_add_f32_e32 v11, v11, v39
	v_add_f32_e32 v12, v12, v40
	v_add_f32_e32 v13, v13, v41
	v_add_f32_e32 v14, v14, v42
	v_add_f32_e32 v15, v15, v43
	v_add_f32_e32 v16, v16, v44
	v_add_f32_e32 v17, v17, v45
	v_add_f32_e32 v18, v18, v46
	v_add_f32_e32 v19, v19, v47
	v_add_f32_e32 v20, v20, v48
	v_add_f32_e32 v21, v21, v49
	v_add_f32_e32 v22, v22, v50
	v_add_f32_e32 v23, v23, v51
	s_waitcnt lgkmcnt(6)
	v_add_f32_e32 v0, v0, v52
	v_add_f32_e32 v1, v1, v53
	v_add_f32_e32 v2, v2, v54
	v_add_f32_e32 v3, v3, v55
	v_add_f32_e32 v4, v4, v56
	v_add_f32_e32 v5, v5, v57
	v_add_f32_e32 v6, v6, v58
	v_add_f32_e32 v7, v7, v59
	v_add_f32_e32 v8, v8, v60
	v_add_f32_e32 v9, v9, v61
	v_add_f32_e32 v10, v10, v62
	v_add_f32_e32 v11, v11, v63
	v_add_f32_e32 v12, v12, v64
	v_add_f32_e32 v13, v13, v65
	v_add_f32_e32 v14, v14, v66
	v_add_f32_e32 v15, v15, v67
	v_add_f32_e32 v16, v16, v68
	v_add_f32_e32 v17, v17, v69
	v_add_f32_e32 v18, v18, v70
	v_add_f32_e32 v19, v19, v71
	v_add_f32_e32 v20, v20, v72
	v_add_f32_e32 v21, v21, v73
	v_add_f32_e32 v22, v22, v74
	v_add_f32_e32 v23, v23, v75
	s_waitcnt lgkmcnt(0)
	v_add_f32_e32 v0, v0, v76
	v_add_f32_e32 v1, v1, v77
	v_add_f32_e32 v2, v2, v78
	v_add_f32_e32 v3, v3, v79
	v_add_f32_e32 v4, v4, v80
	v_add_f32_e32 v5, v5, v81
	v_add_f32_e32 v6, v6, v82
	v_add_f32_e32 v7, v7, v83
	v_add_f32_e32 v8, v8, v84
	v_add_f32_e32 v9, v9, v85
	v_add_f32_e32 v10, v10, v86
	v_add_f32_e32 v11, v11, v87
	v_add_f32_e32 v12, v12, v88
	v_add_f32_e32 v13, v13, v89
	v_add_f32_e32 v14, v14, v90
	v_add_f32_e32 v15, v15, v91
	v_add_f32_e32 v16, v16, v92
	v_add_f32_e32 v17, v17, v93
	v_add_f32_e32 v18, v18, v94
	v_add_f32_e32 v19, v19, v95
	v_add_f32_e32 v20, v20, v96
	v_add_f32_e32 v21, v21, v97
	v_add_f32_e32 v22, v22, v98
	v_add_f32_e32 v23, v23, v99
	s_branch .Lg2_win_epiK
.Lg2_win_sd_clr:
	v_mov_b32_e32 v0, 0
	v_mov_b32_e32 v1, 0
	v_mov_b32_e32 v2, 0
	v_mov_b32_e32 v3, 0
	v_mov_b32_e32 v4, 0
	v_mov_b32_e32 v5, 0
	v_mov_b32_e32 v6, 0
	v_mov_b32_e32 v7, 0
	v_mov_b32_e32 v8, 0
	v_mov_b32_e32 v9, 0
	v_mov_b32_e32 v10, 0
	v_mov_b32_e32 v11, 0
	v_mov_b32_e32 v12, 0
	v_mov_b32_e32 v13, 0
	v_mov_b32_e32 v14, 0
	v_mov_b32_e32 v15, 0
	v_mov_b32_e32 v16, 0
	v_mov_b32_e32 v17, 0
	v_mov_b32_e32 v18, 0
	v_mov_b32_e32 v19, 0
	v_mov_b32_e32 v20, 0
	v_mov_b32_e32 v21, 0
	v_mov_b32_e32 v22, 0
	v_mov_b32_e32 v23, 0
	s_branch .Lg2_win_epiK
